# v39: P7 merge epilogue issues all 16 gate loads before the first wait (was: 10 loads, vmcnt(0), 6 loads)
# speedup vs baseline: 1.0032x; 1.0032x over previous
; __device__ __forceinline__ u32x4 pack8(const f32x4 a, const f32x4 b) { u32x4 w; w.x = cvtpk(a[0], a[1]); w.y = cvtpk(a[2], a[3]); w.z = cvtpk(b[0], b[1]); w.w = cvtpk(b[2], b[3]); return w; }
; __device__ __forceinline__ void unpack8(const u32x4 w, f32x4& a, f32x4& b) { a = (f32x4){bflo(w.x), bfhi(w.x), bflo(w.y), bfhi(w.y)}; b = (f32x4){bflo(w.z), bfhi(w.z), bflo(w.w), bfhi(w.w)}; }
;     __device__ __forceinline__ void operator()(Acc& acc, const Unit& u, int wr, int wc, int fr, int fq) const {
;         const size_t off0 = (size_t)(u.pm * BM + wr * 64 + fr) * 2048 + u.pn * BM + wc * 32 + 8 * fq + (u.part ? 1024 : 0);
;         u32x4 gw[2][4][2];
; #pragma unroll
;         for (int ai = 0; ai < 2; ++ai)
; #pragma unroll
;             for (int m = 0; m < 4; ++m)
; #pragma unroll
;                 for (int bj = 0; bj < 2; ++bj) gw[ai][m][bj] = *(const u32x4*)(G + off0 + (size_t)(ai * HALF + m * 16) * 2048 + bj * HALF);
; #pragma unroll
;         for (int ai = 0; ai < 2; ++ai)
; #pragma unroll
;             for (int m = 0; m < 4; ++m) {
;                 const int row = u.pm * BM + ai * HALF + wr * 64 + m * 16 + fr;
; #pragma unroll
;                 for (int bj = 0; bj < 2; ++bj) {
;                     f32x4 a0, a1; unpack8(gw[ai][m][bj], a0, a1);
;                     if (u.part == 0) { acc[ai][bj][m][0] *= a0; acc[ai][bj][m][1] *= a1; }
;                     else {
;                         bf16_t* po = Go + (size_t)(row & omask) * 2048 + u.pn * BM + bj * HALF + wc * 32 + 8 * fq;
;                         *(u32x4*)po = pack8(a0 * acc[ai][bj][m][0], a1 * acc[ai][bj][m][1]);
;                     }
;                 }
.LBB0_1416:
	s_lshl_b32 s19, s28, 8
	v_add_u32_e32 v218, s19, v224
	v_ashrrev_i32_e32 v219, 31, v218
	s_lshl_b32 s28, s6, 8
	v_lshlrev_b64 v[130:131], 12, v[218:219]
	s_ashr_i32 s29, s28, 31
	v_lshl_add_u64 v[130:131], s[94:95], 0, v[130:131]
	s_cmp_lg_u32 s7, 0
	v_lshl_add_u64 v[130:131], s[28:29], 1, v[130:131]
	s_cselect_b64 s[30:31], -1, 0
	s_cmp_eq_u32 s7, 0
	v_lshl_add_u64 v[130:131], v[130:131], 0, s[10:11]
	s_cselect_b32 s6, 0, 0x800
	s_mov_b32 s7, s11
	v_lshl_add_u64 v[130:131], v[130:131], 0, v[208:209]
	v_lshl_add_u64 v[130:131], v[130:131], 0, s[6:7]
	s_mov_b32 s6, 0x10000
	v_add_co_u32_e32 v132, vcc, s6, v130
	s_mov_b32 s6, 0x20000
	s_nop 0
	v_addc_co_u32_e32 v133, vcc, 0, v131, vcc
	global_load_dwordx4 v[192:195], v[130:131], off
	global_load_dwordx4 v[186:189], v[130:131], off offset:256
	global_load_dwordx4 v[182:185], v[132:133], off
	global_load_dwordx4 v[178:181], v[132:133], off offset:256
	v_add_co_u32_e32 v132, vcc, s6, v130
	s_mov_b32 s6, 0x30000
	s_nop 0
	v_addc_co_u32_e32 v133, vcc, 0, v131, vcc
	global_load_dwordx4 v[174:177], v[132:133], off
	global_load_dwordx4 v[170:173], v[132:133], off offset:256
	v_add_co_u32_e32 v132, vcc, s6, v130
	s_mov_b64 s[6:7], -1
	s_nop 0
	v_addc_co_u32_e32 v133, vcc, 0, v131, vcc
	global_load_dwordx4 v[166:169], v[132:133], off
	global_load_dwordx4 v[162:165], v[132:133], off offset:256
	v_add_co_u32_e32 v132, vcc, s54, v130
	v_and_b32_e32 v220, 0x7fffffcf, v218
	s_nop 0
	v_addc_co_u32_e32 v133, vcc, 0, v131, vcc
	global_load_dwordx4 v[158:161], v[132:133], off
	global_load_dwordx4 v[154:157], v[132:133], off offset:256
	v_add_co_u32_e32 v132, vcc, s55, v130
	s_nop 1
	v_addc_co_u32_e32 v133, vcc, 0, v131, vcc
	global_load_dwordx4 v[150:153], v[132:133], off
	global_load_dwordx4 v[146:149], v[132:133], off offset:256
	v_add_co_u32_e32 v132, vcc, s56, v130
	s_nop 1
	v_addc_co_u32_e32 v133, vcc, 0, v131, vcc
	v_add_co_u32_e32 v130, vcc, s57, v130
	global_load_dwordx4 v[142:145], v[132:133], off
	global_load_dwordx4 v[138:141], v[132:133], off offset:256
	v_addc_co_u32_e32 v131, vcc, 0, v131, vcc
	global_load_dwordx4 v[134:137], v[130:131], off
	s_nop 0
	global_load_dwordx4 v[130:133], v[130:131], off offset:256
	s_waitcnt vmcnt(6)
	v_lshlrev_b32_e32 v190, 16, v192
	v_and_b32_e32 v191, 0xffff0000, v192
	v_lshlrev_b32_e32 v230, 16, v194
	v_and_b32_e32 v231, 0xffff0000, v194
	s_and_b64 vcc, exec, s[30:31]
	v_lshlrev_b32_e32 v192, 16, v193
	v_and_b32_e32 v193, 0xffff0000, v193
	v_lshlrev_b32_e32 v196, 16, v195
	v_and_b32_e32 v197, 0xffff0000, v195
	v_pk_mul_f32 v[190:191], v[126:127], v[190:191]
	v_pk_mul_f32 v[194:195], v[110:111], v[230:231]
	s_cbranch_vccz .LBB0_1418
	v_mov_b32_e32 v221, v209
	v_lshlrev_b64 v[230:231], 12, v[220:221]
	v_lshl_add_u64 v[230:231], s[94:95], 0, v[230:231]
	v_lshl_add_u64 v[230:231], s[28:29], 1, v[230:231]
	v_lshl_add_u64 v[230:231], v[230:231], 0, s[10:11]
	v_pk_mul_f32 v[232:233], v[128:129], v[192:193]
	v_pk_mul_f32 v[236:237], v[112:113], v[196:197]
	v_lshl_add_u64 v[234:235], v[230:231], 0, v[208:209]
	v_cvt_pk_bf16_f32 v230, v190, v191
	v_cvt_pk_bf16_f32 v231, v232, v233
	v_cvt_pk_bf16_f32 v232, v194, v195
	v_cvt_pk_bf16_f32 v233, v236, v237
	global_store_dwordx4 v[234:235], v[230:233], off
	s_mov_b64 s[6:7], 0
